# v26 + attention loops: softmax row sums via v_dot2c_f32_bf16 against the ones word (same bf16 P fragments, f32 accumulate) + one permlane32 cross-half add, replacing 4 extra 32x32x16 ones-MFMAs per kv
# baseline (speedup 1.0000x reference)
.LBB0_738:
	v_cvt_pk_bf16_f32 v50, v50, v51
	v_cvt_pk_bf16_f32 v51, v52, v53
	v_cvt_pk_bf16_f32 v52, v54, v182
	v_cvt_pk_bf16_f32 v53, v56, v183
	v_cvt_pk_bf16_f32 v54, v55, v57
	v_cvt_pk_bf16_f32 v55, v58, v59
	v_mov_b32_e32 v82, 0
	v_dot2c_f32_bf16_e32 v82, v50, v198
	v_dot2c_f32_bf16_e32 v82, v51, v198
	v_dot2c_f32_bf16_e32 v82, v52, v198
	v_dot2c_f32_bf16_e32 v82, v53, v198
	v_cvt_pk_bf16_f32 v56, v60, v61
	v_cvt_pk_bf16_f32 v57, v62, v63
	v_mfma_f32_32x32x16_bf16 v[2:17], v[170:173], v[50:53], v[2:17]
	ds_read_b64_tr_b16 v[58:59], v221 offset:28672
	ds_read_b64_tr_b16 v[60:61], v221 offset:29184
	v_exp_f32_e32 v62, v34
	v_exp_f32_e32 v63, v35
	v_exp_f32_e32 v64, v36
	v_exp_f32_e32 v65, v37
	v_mfma_f32_32x32x16_bf16 v[18:33], v[166:169], v[50:53], v[18:33]
	ds_read_b64_tr_b16 v[34:35], v221 offset:32768
	ds_read_b64_tr_b16 v[36:37], v221 offset:33280
	v_exp_f32_e32 v50, v38
	v_exp_f32_e32 v51, v39
	v_exp_f32_e32 v52, v40
	v_exp_f32_e32 v41, v41
	v_dot2c_f32_bf16_e32 v82, v54, v198
	v_dot2c_f32_bf16_e32 v82, v55, v198
	v_dot2c_f32_bf16_e32 v82, v56, v198
	v_dot2c_f32_bf16_e32 v82, v57, v198
	v_cvt_pk_bf16_f32 v38, v62, v63
	v_cvt_pk_bf16_f32 v39, v64, v65
	v_cvt_pk_bf16_f32 v40, v50, v51
	v_cvt_pk_bf16_f32 v41, v52, v41
	s_waitcnt lgkmcnt(6)
	v_mfma_f32_32x32x16_bf16 v[2:17], v[178:181], v[54:57], v[2:17]
	ds_read_b64_tr_b16 v[50:51], v221 offset:29696
	ds_read_b64_tr_b16 v[52:53], v221 offset:30208
	v_exp_f32_e32 v62, v42
	v_exp_f32_e32 v63, v43
	v_exp_f32_e32 v64, v44
	v_exp_f32_e32 v65, v45
	s_waitcnt lgkmcnt(6)
	v_mfma_f32_32x32x16_bf16 v[18:33], v[174:177], v[54:57], v[18:33]
	ds_read_b64_tr_b16 v[42:43], v221 offset:33792
	ds_read_b64_tr_b16 v[44:45], v221 offset:34304
	v_exp_f32_e32 v54, v46
	v_exp_f32_e32 v55, v47
	v_exp_f32_e32 v56, v48
	v_exp_f32_e32 v49, v49
	v_dot2c_f32_bf16_e32 v82, v38, v198
	v_dot2c_f32_bf16_e32 v82, v39, v198
	v_dot2c_f32_bf16_e32 v82, v40, v198
	v_dot2c_f32_bf16_e32 v82, v41, v198
	v_cvt_pk_bf16_f32 v46, v62, v63
	v_cvt_pk_bf16_f32 v47, v64, v65
	v_cvt_pk_bf16_f32 v48, v54, v55
	v_cvt_pk_bf16_f32 v49, v56, v49
	s_and_saveexec_b64 s[0:1], s[44:45]
	s_cbranch_execz .LBB0_740
	s_waitcnt vmcnt(2)
	ds_write_b128 v195, v[162:165]

.LBB0_742:
	s_or_b64 exec, exec, s[0:1]
	s_waitcnt lgkmcnt(5)
	v_mfma_f32_32x32x16_bf16 v[18:33], v[34:37], v[38:41], v[18:33]
	v_dot2c_f32_bf16_e32 v82, v46, v198
	v_dot2c_f32_bf16_e32 v82, v47, v198
	v_dot2c_f32_bf16_e32 v82, v48, v198
	v_dot2c_f32_bf16_e32 v82, v49, v198
	s_nop 2
	v_mov_b32_e32 v83, v82
	s_nop 1
	v_permlane32_swap_b32_e32 v82, v83
	v_add_f32_e32 v82, v82, v83
	s_waitcnt vmcnt(0)
	ds_write_b128 v217, v[154:157] offset:34816
	s_waitcnt lgkmcnt(4)
	v_mfma_f32_32x32x16_bf16 v[2:17], v[50:53], v[46:49], v[2:17]
	s_waitcnt lgkmcnt(2)
	v_mfma_f32_32x32x16_bf16 v[18:33], v[42:45], v[46:49], v[18:33]
	s_and_b64 vcc, exec, s[14:15]
	s_waitcnt lgkmcnt(0)
	s_barrier
	s_cbranch_vccz .LBB0_744
	v_sub_f32_e32 v113, v113, v190
	v_sub_f32_e32 v112, v112, v190
	v_sub_f32_e32 v111, v111, v190
	v_sub_f32_e32 v110, v110, v190
	v_sub_f32_e32 v109, v109, v190
	v_sub_f32_e32 v108, v108, v190
	v_sub_f32_e32 v107, v107, v190
	v_sub_f32_e32 v106, v106, v190
	v_sub_f32_e32 v105, v105, v190
	v_sub_f32_e32 v104, v104, v190
	v_sub_f32_e32 v103, v103, v190
	v_sub_f32_e32 v102, v102, v190
	v_sub_f32_e32 v101, v101, v190
	v_sub_f32_e32 v100, v100, v190
	v_sub_f32_e32 v99, v99, v190
	v_sub_f32_e32 v98, v98, v190
	v_sub_f32_e32 v81, v81, v190
	v_sub_f32_e32 v80, v80, v190
	v_sub_f32_e32 v79, v79, v190
	v_sub_f32_e32 v78, v78, v190
	v_sub_f32_e32 v77, v77, v190
	v_sub_f32_e32 v76, v76, v190
	v_sub_f32_e32 v75, v75, v190
	v_sub_f32_e32 v74, v74, v190
	v_sub_f32_e32 v73, v73, v190
	v_sub_f32_e32 v72, v72, v190
	v_sub_f32_e32 v71, v71, v190
	v_sub_f32_e32 v70, v70, v190
	v_sub_f32_e32 v69, v69, v190
	v_sub_f32_e32 v68, v68, v190
	v_sub_f32_e32 v67, v67, v190
	v_sub_f32_e32 v66, v66, v190

.LBB0_749:
	v_cvt_pk_bf16_f32 v108, v96, v97
	v_cvt_pk_bf16_f32 v109, v98, v99
	v_cvt_pk_bf16_f32 v110, v100, v102
	v_cvt_pk_bf16_f32 v111, v103, v186
	v_cvt_pk_bf16_f32 v102, v84, v85
	v_cvt_pk_bf16_f32 v103, v86, v87
	v_mov_b32_e32 v84, 0
	v_dot2c_f32_bf16_e32 v84, v108, v198
	v_dot2c_f32_bf16_e32 v84, v109, v198
	v_dot2c_f32_bf16_e32 v84, v110, v198
	v_dot2c_f32_bf16_e32 v84, v111, v198
	v_cvt_pk_bf16_f32 v100, v101, v104
	v_cvt_pk_bf16_f32 v101, v105, v106
	v_mfma_f32_32x32x16_bf16 v[2:17], v[170:173], v[108:111], v[2:17]
	ds_read_b64_tr_b16 v[104:105], v221 offset:36864
	ds_read_b64_tr_b16 v[106:107], v221 offset:37376
	v_exp_f32_e32 v112, v66
	v_exp_f32_e32 v113, v67
	v_exp_f32_e32 v170, v68
	v_exp_f32_e32 v171, v69
	v_mfma_f32_32x32x16_bf16 v[18:33], v[166:169], v[108:111], v[18:33]
	ds_read_b64_tr_b16 v[66:67], v221 offset:40960
	ds_read_b64_tr_b16 v[68:69], v221 offset:41472
	v_exp_f32_e32 v108, v70
	v_exp_f32_e32 v109, v71
	v_exp_f32_e32 v110, v72
	v_exp_f32_e32 v73, v73
	v_dot2c_f32_bf16_e32 v84, v100, v198
	v_dot2c_f32_bf16_e32 v84, v101, v198
	v_dot2c_f32_bf16_e32 v84, v102, v198
	v_dot2c_f32_bf16_e32 v84, v103, v198
	v_cvt_pk_bf16_f32 v70, v112, v113
	v_cvt_pk_bf16_f32 v71, v170, v171
	v_cvt_pk_bf16_f32 v72, v108, v109
	v_cvt_pk_bf16_f32 v73, v110, v73
	s_waitcnt lgkmcnt(6)
	v_mfma_f32_32x32x16_bf16 v[2:17], v[178:181], v[100:103], v[2:17]
	ds_read_b64_tr_b16 v[108:109], v221 offset:37888
	ds_read_b64_tr_b16 v[110:111], v221 offset:38400
	v_exp_f32_e32 v112, v74
	v_exp_f32_e32 v113, v75
	v_exp_f32_e32 v166, v76
	v_exp_f32_e32 v167, v77
	s_waitcnt lgkmcnt(6)
	v_mfma_f32_32x32x16_bf16 v[18:33], v[174:177], v[100:103], v[18:33]
	ds_read_b64_tr_b16 v[74:75], v221 offset:41984
	ds_read_b64_tr_b16 v[76:77], v221 offset:42496
	v_exp_f32_e32 v100, v78
	v_exp_f32_e32 v101, v79
	v_exp_f32_e32 v102, v80
	v_exp_f32_e32 v81, v81
	v_dot2c_f32_bf16_e32 v84, v70, v198
	v_dot2c_f32_bf16_e32 v84, v71, v198
	v_dot2c_f32_bf16_e32 v84, v72, v198
	v_dot2c_f32_bf16_e32 v84, v73, v198
	v_cvt_pk_bf16_f32 v78, v112, v113
	v_cvt_pk_bf16_f32 v79, v166, v167
	v_cvt_pk_bf16_f32 v80, v100, v101
	v_cvt_pk_bf16_f32 v81, v102, v81
	s_and_saveexec_b64 s[0:1], s[44:45]
	s_cbranch_execz .LBB0_751
	s_waitcnt vmcnt(2)
	ds_write_b128 v195, v[162:165] offset:13312

.LBB0_753:
	s_or_b64 exec, exec, s[0:1]
	s_waitcnt lgkmcnt(5)
	v_mfma_f32_32x32x16_bf16 v[18:33], v[66:69], v[70:73], v[18:33]
	v_dot2c_f32_bf16_e32 v84, v78, v198
	v_dot2c_f32_bf16_e32 v84, v79, v198
	v_dot2c_f32_bf16_e32 v84, v80, v198
	v_dot2c_f32_bf16_e32 v84, v81, v198
	s_nop 2
	v_mov_b32_e32 v85, v84
	s_nop 1
	v_permlane32_swap_b32_e32 v84, v85
	v_add_f32_e32 v84, v84, v85
	s_waitcnt vmcnt(0)
	ds_write_b128 v217, v[154:157] offset:26624
	s_waitcnt lgkmcnt(4)
	v_mfma_f32_32x32x16_bf16 v[2:17], v[108:111], v[78:81], v[2:17]
	s_waitcnt lgkmcnt(2)
	v_mfma_f32_32x32x16_bf16 v[18:33], v[74:77], v[78:81], v[18:33]
	v_fmac_f32_e32 v82, v222, v0
	s_mov_b64 s[0:1], 0x80000
	v_cndmask_b32_e64 v191, v223, v83, s[48:49]
	s_cmp_lt_u32 s16, 30
	v_lshl_add_u64 v[214:215], v[214:215], 0, s[0:1]
	s_nop 1
	v_fmac_f32_e32 v84, v82, v218
	s_waitcnt lgkmcnt(0)
	s_barrier
	s_cbranch_scc0 .LBB0_714
	v_mov_b32_e32 v222, v84
	s_andn2_b64 vcc, exec, s[14:15]
	s_cbranch_vccz .LBB0_732
	s_branch .LBB0_733

.LBB0_830:
	v_fmac_f32_e32 v50, v34, v0
	v_cvt_pk_bf16_f32 v118, v35, v48
	v_cvt_pk_bf16_f32 v119, v49, v128
	v_cvt_pk_bf16_f32 v120, v44, v45
	v_cvt_pk_bf16_f32 v121, v46, v47
	s_mov_b32 s38, s36
	s_mov_b32 s39, s36
	s_mov_b32 s37, s36
	v_mov_b64_e32 v[146:147], s[38:39]
	v_mov_b64_e32 v[144:145], s[36:37]
	v_cvt_pk_bf16_f32 v148, v40, v41
	v_cvt_pk_bf16_f32 v149, v42, v43
	v_cvt_pk_bf16_f32 v150, v36, v37
	v_cvt_pk_bf16_f32 v151, v38, v39
	v_mov_b32_e32 v34, 0
	v_dot2c_f32_bf16_e32 v34, v118, v144
	v_dot2c_f32_bf16_e32 v34, v119, v144
	v_dot2c_f32_bf16_e32 v34, v120, v144
	v_dot2c_f32_bf16_e32 v34, v121, v144
	s_waitcnt lgkmcnt(6)
	v_mfma_f32_32x32x16_bf16 v[2:17], v[114:117], v[118:121], v[2:17]
	v_add_u32_e32 v0, 0x14800, v126
	ds_read_b64_tr_b16 v[114:115], v0
	v_add_u32_e32 v0, 0x14a00, v126
	ds_read_b64_tr_b16 v[116:117], v0
	v_sub_f32_e32 v0, v51, v143
	v_sub_f32_e32 v51, v129, v143
	v_sub_f32_e32 v128, v134, v143
	v_sub_f32_e32 v129, v135, v143
	v_exp_f32_e32 v0, v0
	v_exp_f32_e32 v51, v51
	v_exp_f32_e32 v128, v128
	v_exp_f32_e32 v129, v129
	s_waitcnt lgkmcnt(6)
	v_mfma_f32_32x32x16_bf16 v[18:33], v[88:91], v[118:121], v[18:33]
	v_add_u32_e32 v88, 0x15800, v126
	v_add_u32_e32 v90, 0x15a00, v126
	v_sub_f32_e32 v118, v130, v143
	ds_read_b64_tr_b16 v[88:89], v88
	ds_read_b64_tr_b16 v[90:91], v90
	v_exp_f32_e32 v120, v118
	v_sub_f32_e32 v118, v131, v143
	v_exp_f32_e32 v121, v118
	v_sub_f32_e32 v118, v136, v143
	v_exp_f32_e32 v130, v118
	v_sub_f32_e32 v118, v137, v143
	v_exp_f32_e32 v131, v118
	v_dot2c_f32_bf16_e32 v34, v148, v144
	v_dot2c_f32_bf16_e32 v34, v149, v144
	v_dot2c_f32_bf16_e32 v34, v150, v144
	v_dot2c_f32_bf16_e32 v34, v151, v144
	v_cvt_pk_bf16_f32 v118, v0, v51
	v_cvt_pk_bf16_f32 v119, v128, v129
	v_cvt_pk_bf16_f32 v120, v120, v121
	v_cvt_pk_bf16_f32 v121, v130, v131
	s_waitcnt lgkmcnt(6)
	v_mfma_f32_32x32x16_bf16 v[2:17], v[92:95], v[148:151], v[2:17]
	v_add_u32_e32 v0, 0x14c00, v126
	ds_read_b64_tr_b16 v[92:93], v0
	v_add_u32_e32 v0, 0x14e00, v126
	ds_read_b64_tr_b16 v[94:95], v0
	v_sub_f32_e32 v128, v140, v143
	v_sub_f32_e32 v0, v132, v143
	v_sub_f32_e32 v51, v133, v143
	v_exp_f32_e32 v129, v128
	v_sub_f32_e32 v128, v141, v143
	v_exp_f32_e32 v0, v0
	v_exp_f32_e32 v51, v51
	v_exp_f32_e32 v130, v128
	s_waitcnt lgkmcnt(6)
	v_mfma_f32_32x32x16_bf16 v[18:33], v[84:87], v[148:151], v[18:33]
	v_add_u32_e32 v84, 0x15c00, v126
	v_add_u32_e32 v86, 0x15e00, v126
	ds_read_b64_tr_b16 v[84:85], v84
	ds_read_b64_tr_b16 v[86:87], v86
	v_sub_f32_e32 v128, v139, v143
	v_sub_f32_e32 v126, v138, v143
	v_exp_f32_e32 v131, v128
	v_sub_f32_e32 v128, v142, v143
	v_sub_f32_e32 v97, v97, v143
	v_exp_f32_e32 v126, v126
	v_exp_f32_e32 v132, v128
	v_exp_f32_e32 v97, v97
	v_dot2c_f32_bf16_e32 v34, v118, v144
	v_dot2c_f32_bf16_e32 v34, v119, v144
	v_dot2c_f32_bf16_e32 v34, v120, v144
	v_dot2c_f32_bf16_e32 v34, v121, v144
	v_cvt_pk_bf16_f32 v128, v0, v51
	v_cvt_pk_bf16_f32 v129, v129, v130
	v_cvt_pk_bf16_f32 v130, v126, v131
	v_cvt_pk_bf16_f32 v131, v132, v97
	s_waitcnt lgkmcnt(6)
	v_mfma_f32_32x32x16_bf16 v[2:17], v[114:117], v[118:121], v[2:17]
	s_waitcnt lgkmcnt(4)
	v_mfma_f32_32x32x16_bf16 v[18:33], v[88:91], v[118:121], v[18:33]
	v_dot2c_f32_bf16_e32 v34, v128, v144
	v_dot2c_f32_bf16_e32 v34, v129, v144
	v_dot2c_f32_bf16_e32 v34, v130, v144
	v_dot2c_f32_bf16_e32 v34, v131, v144
	s_nop 2
	v_mov_b32_e32 v35, v34
	s_nop 1
	v_permlane32_swap_b32_e32 v34, v35
	v_add_f32_e32 v34, v34, v35
	s_waitcnt lgkmcnt(2)
	v_mfma_f32_32x32x16_bf16 v[2:17], v[92:95], v[128:131], v[2:17]
	s_waitcnt lgkmcnt(0)
	v_mfma_f32_32x32x16_bf16 v[18:33], v[84:87], v[128:131], v[18:33]
	s_nop 7
	v_fmac_f32_e32 v34, v50, v96
	v_add_u32_e32 v124, 0x4000, v124
	s_cmp_lt_u32 s12, s22
	v_add_u32_e32 v125, 0x200, v125
	s_cbranch_scc0 .LBB0_820

.LBB0_835:
	v_cvt_pk_bf16_f32 v142, v127, v142
	v_cvt_pk_bf16_f32 v143, v143, v144
	v_cvt_pk_bf16_f32 v144, v56, v57
	v_cvt_pk_bf16_f32 v145, v58, v59
	s_mov_b32 s38, s36
	s_mov_b32 s39, s36
	s_mov_b32 s37, s36
	v_mov_b64_e32 v[148:149], s[38:39]
	v_mov_b64_e32 v[146:147], s[36:37]
	v_cvt_pk_bf16_f32 v150, v52, v53
	v_cvt_pk_bf16_f32 v151, v54, v55
	v_cvt_pk_bf16_f32 v153, v50, v51
	v_mov_b32_e32 v50, 0
	v_dot2c_f32_bf16_e32 v50, v142, v146
	v_dot2c_f32_bf16_e32 v50, v143, v146
	v_dot2c_f32_bf16_e32 v50, v144, v146
	v_dot2c_f32_bf16_e32 v50, v145, v146
	v_cvt_pk_bf16_f32 v152, v48, v49
	s_waitcnt lgkmcnt(6)
	v_mfma_f32_32x32x16_bf16 v[2:17], v[114:117], v[142:145], v[2:17]
	v_add_u32_e32 v48, 0x12800, v126
	ds_read_b64_tr_b16 v[114:115], v48
	v_add_u32_e32 v48, 0x12a00, v126
	ds_read_b64_tr_b16 v[116:117], v48
	v_sub_f32_e32 v48, v118, v141
	v_sub_f32_e32 v118, v131, v141
	v_sub_f32_e32 v49, v119, v141
	v_exp_f32_e32 v119, v118
	v_sub_f32_e32 v118, v132, v141
	v_exp_f32_e32 v48, v48
	v_exp_f32_e32 v49, v49
	v_exp_f32_e32 v127, v118
	s_waitcnt lgkmcnt(6)
	v_mfma_f32_32x32x16_bf16 v[18:33], v[44:47], v[142:145], v[18:33]
	v_add_u32_e32 v44, 0x13800, v126
	v_add_u32_e32 v46, 0x13a00, v126
	ds_read_b64_tr_b16 v[44:45], v44
	ds_read_b64_tr_b16 v[46:47], v46
	v_sub_f32_e32 v118, v120, v141
	v_exp_f32_e32 v120, v118
	v_sub_f32_e32 v118, v121, v141
	v_exp_f32_e32 v121, v118
	v_sub_f32_e32 v118, v133, v141
	v_exp_f32_e32 v131, v118
	v_sub_f32_e32 v118, v134, v141
	v_exp_f32_e32 v132, v118
	v_dot2c_f32_bf16_e32 v50, v150, v146
	v_dot2c_f32_bf16_e32 v50, v151, v146
	v_dot2c_f32_bf16_e32 v50, v152, v146
	v_dot2c_f32_bf16_e32 v50, v153, v146
	v_cvt_pk_bf16_f32 v118, v48, v49
	v_cvt_pk_bf16_f32 v119, v119, v127
	v_cvt_pk_bf16_f32 v120, v120, v121
	v_cvt_pk_bf16_f32 v121, v131, v132
	s_waitcnt lgkmcnt(6)
	v_mfma_f32_32x32x16_bf16 v[2:17], v[40:43], v[150:153], v[2:17]
	v_add_u32_e32 v40, 0x12c00, v126
	v_add_u32_e32 v42, 0x12e00, v126
	ds_read_b64_tr_b16 v[40:41], v40
	ds_read_b64_tr_b16 v[42:43], v42
	v_sub_f32_e32 v48, v129, v141
	v_sub_f32_e32 v49, v130, v141
	v_sub_f32_e32 v127, v137, v141
	v_sub_f32_e32 v129, v138, v141
	v_exp_f32_e32 v48, v48
	v_exp_f32_e32 v49, v49
	v_exp_f32_e32 v127, v127
	v_exp_f32_e32 v129, v129
	s_waitcnt lgkmcnt(6)
	v_mfma_f32_32x32x16_bf16 v[18:33], v[36:39], v[150:153], v[18:33]
	v_add_u32_e32 v36, 0x13c00, v126
	v_add_u32_e32 v38, 0x13e00, v126
	ds_read_b64_tr_b16 v[36:37], v36
	ds_read_b64_tr_b16 v[38:39], v38
	v_sub_f32_e32 v130, v135, v141
	v_exp_f32_e32 v132, v130
	v_sub_f32_e32 v130, v136, v141
	v_exp_f32_e32 v133, v130
	v_sub_f32_e32 v130, v139, v141
	v_exp_f32_e32 v134, v130
	v_sub_f32_e32 v130, v140, v141
	v_exp_f32_e32 v135, v130
	v_dot2c_f32_bf16_e32 v50, v118, v146
	v_dot2c_f32_bf16_e32 v50, v119, v146
	v_dot2c_f32_bf16_e32 v50, v120, v146
	v_dot2c_f32_bf16_e32 v50, v121, v146
	v_cvt_pk_bf16_f32 v130, v48, v49
	v_cvt_pk_bf16_f32 v131, v127, v129
	v_cvt_pk_bf16_f32 v132, v132, v133
	v_cvt_pk_bf16_f32 v133, v134, v135
	s_waitcnt lgkmcnt(6)
	v_mfma_f32_32x32x16_bf16 v[2:17], v[114:117], v[118:121], v[2:17]
	s_waitcnt lgkmcnt(4)
	v_mfma_f32_32x32x16_bf16 v[18:33], v[44:47], v[118:121], v[18:33]
	v_dot2c_f32_bf16_e32 v50, v130, v146
	v_dot2c_f32_bf16_e32 v50, v131, v146
	v_dot2c_f32_bf16_e32 v50, v132, v146
	v_dot2c_f32_bf16_e32 v50, v133, v146
	s_nop 2
	v_mov_b32_e32 v51, v50
	s_nop 1
	v_permlane32_swap_b32_e32 v50, v51
	v_add_f32_e32 v50, v50, v51
	s_waitcnt lgkmcnt(2)
	v_mfma_f32_32x32x16_bf16 v[2:17], v[40:43], v[130:133], v[2:17]
	s_waitcnt lgkmcnt(0)
	v_mfma_f32_32x32x16_bf16 v[18:33], v[36:39], v[130:133], v[18:33]
	v_add_u32_e32 v36, 0x22600, v35
	ds_read2_b32 v[36:37], v36 offset1:1
	s_waitcnt lgkmcnt(0)
	v_add_f32_e32 v48, v66, v36
	v_add_u32_e32 v36, 0x22680, v35
	ds_read2_b32 v[38:39], v36 offset1:1
	v_add_u32_e32 v36, 0x22608, v35
	v_add_f32_e32 v49, v67, v37
	ds_read2_b32 v[36:37], v36 offset1:1
	s_waitcnt lgkmcnt(1)
	v_add_f32_e32 v51, v82, v38
	v_add_f32_e32 v129, v83, v39
	s_waitcnt lgkmcnt(0)
	v_add_f32_e32 v144, v68, v36
	v_add_u32_e32 v36, 0x22688, v35
	ds_read2_b32 v[38:39], v36 offset1:1
	v_add_u32_e32 v36, 0x22620, v35
	v_add_f32_e32 v146, v69, v37
	ds_read2_b32 v[36:37], v36 offset1:1
	s_waitcnt lgkmcnt(1)
	v_add_f32_e32 v134, v84, v38
	v_add_f32_e32 v135, v85, v39
	s_waitcnt lgkmcnt(0)
	v_add_f32_e32 v145, v70, v36
	v_add_u32_e32 v36, 0x226a0, v35
	ds_read2_b32 v[38:39], v36 offset1:1
	v_add_u32_e32 v36, 0x22628, v35
	v_add_f32_e32 v147, v71, v37
	ds_read2_b32 v[36:37], v36 offset1:1
	s_waitcnt lgkmcnt(1)
	v_add_f32_e32 v130, v86, v38
	v_add_f32_e32 v131, v87, v39
	s_waitcnt lgkmcnt(0)
	v_add_f32_e32 v148, v72, v36
	v_add_u32_e32 v36, 0x226a8, v35
	ds_read2_b32 v[38:39], v36 offset1:1
	v_add_u32_e32 v36, 0x22640, v35
	v_add_f32_e32 v150, v73, v37
	ds_read2_b32 v[36:37], v36 offset1:1
	s_waitcnt lgkmcnt(1)
	v_add_f32_e32 v136, v88, v38
	v_add_f32_e32 v137, v89, v39
	s_waitcnt lgkmcnt(0)
	v_add_f32_e32 v149, v74, v36
	v_add_u32_e32 v36, 0x226c0, v35
	ds_read2_b32 v[38:39], v36 offset1:1
	v_add_u32_e32 v36, 0x22648, v35
	v_add_f32_e32 v151, v75, v37
	ds_read2_b32 v[36:37], v36 offset1:1
	s_waitcnt lgkmcnt(1)
	v_add_f32_e32 v132, v90, v38
	v_add_f32_e32 v133, v91, v39
	s_waitcnt lgkmcnt(0)
	v_add_f32_e32 v152, v76, v36
	v_add_u32_e32 v36, 0x226c8, v35
	ds_read2_b32 v[38:39], v36 offset1:1
	v_add_u32_e32 v36, 0x22660, v35
	v_add_f32_e32 v154, v77, v37
	ds_read2_b32 v[36:37], v36 offset1:1
	s_waitcnt lgkmcnt(1)
	v_add_f32_e32 v140, v92, v38
	v_add_f32_e32 v141, v93, v39
	s_waitcnt lgkmcnt(0)
	v_add_f32_e32 v153, v78, v36
	v_add_u32_e32 v36, 0x226e0, v35
	ds_read2_b32 v[38:39], v36 offset1:1
	v_add_u32_e32 v36, 0x22668, v35
	v_add_u32_e32 v35, 0x226e8, v35
	v_add_f32_e32 v155, v79, v37
	ds_read2_b32 v[36:37], v36 offset1:1
	s_waitcnt lgkmcnt(1)
	v_add_f32_e32 v138, v94, v38
	v_add_f32_e32 v139, v95, v39
	ds_read2_b32 v[38:39], v35 offset1:1
	s_waitcnt lgkmcnt(1)
	v_add_f32_e32 v156, v80, v36
	v_add_f32_e32 v157, v81, v37
	s_waitcnt lgkmcnt(0)
	v_add_f32_e32 v142, v96, v38
	v_add_f32_e32 v97, v97, v39
	s_add_i32 s12, s12, 2
	s_min_i32 s4, s12, s28
	s_sub_i32 s4, s4, s20
	s_mulk_i32 s4, 0x2400
	v_add_u32_e32 v36, s4, v123
	ds_read_b128 v[52:55], v36
	ds_read_b128 v[84:87], v36 offset:32
	ds_read_b128 v[68:71], v36 offset:4608
	ds_read_b128 v[118:121], v36 offset:64
	ds_read_b128 v[92:95], v36 offset:4640
	ds_read_b128 v[44:47], v36 offset:4672
	v_add_u32_e32 v35, 0x14000, v126
	v_max3_f32 v37, v240, v48, v49
	v_max3_f32 v38, v240, v144, v146
	s_nop 0
	v_max3_f32 v56, v37, v51, v129
	v_max3_f32 v57, v38, v134, v135
	s_nop 0
	v_max3_f32 v56, v56, v145, v147
	v_max3_f32 v57, v57, v148, v150
	ds_read_b128 v[40:43], v36 offset:96
	ds_read_b128 v[36:39], v36 offset:4704
	v_max3_f32 v72, v56, v130, v131
	v_max3_f32 v73, v57, v136, v137
	s_waitcnt lgkmcnt(7)
	v_mfma_f32_32x32x16_bf16 v[52:67], v[52:55], v[98:101], 0
	v_max3_f32 v72, v72, v149, v151
	v_max3_f32 v73, v73, v152, v154
	s_nop 0
	v_max3_f32 v96, v72, v132, v133
	v_max3_f32 v127, v73, v140, v141
	s_waitcnt lgkmcnt(5)
	v_mfma_f32_32x32x16_bf16 v[68:83], v[68:71], v[98:101], 0
	v_add_u32_e32 v88, 0x14200, v126
	v_add_u32_e32 v89, 0x15000, v126
	v_add_u32_e32 v90, 0x15200, v126
	v_mfma_f32_32x32x16_bf16 v[52:67], v[84:87], v[102:105], v[52:67]
	ds_read_b64_tr_b16 v[114:115], v35
	ds_read_b64_tr_b16 v[116:117], v88
	ds_read_b64_tr_b16 v[88:89], v89
	ds_read_b64_tr_b16 v[90:91], v90
	v_max3_f32 v35, v96, v153, v155
	v_max3_f32 v84, v127, v156, v157
	s_nop 0
	v_max3_f32 v35, v35, v138, v139
	v_max3_f32 v84, v84, v142, v97
	s_waitcnt lgkmcnt(7)
	v_mfma_f32_32x32x16_bf16 v[68:83], v[92:95], v[102:105], v[68:83]
	v_max_f32_e32 v35, v35, v84
	v_mov_b32_e32 v127, v128
	v_mov_b32_e32 v84, v35
	s_nop 1
	v_permlane32_swap_b32_e32 v35, v84
	v_max_f32_e32 v35, v35, v84
	v_add_f32_e32 v84, 0x40a00000, v128
	v_cmp_gt_f32_e32 vcc, v35, v84
	s_cbranch_vccz .LBB0_837
	v_add_f32_e32 v35, 0, v35
	v_max_f32_e32 v127, v128, v35

.LBB0_934:
	v_cvt_pk_bf16_f32 v136, v130, v131
	v_cvt_pk_bf16_f32 v137, v132, v133
	ds_read_b64_tr_b16 v[130:131], v113 offset:18432
	ds_read_b64_tr_b16 v[132:133], v113 offset:18944
	ds_read_b64_tr_b16 v[138:139], v113 offset:22528
	ds_read_b64_tr_b16 v[140:141], v113 offset:23040
	ds_read_b64_tr_b16 v[192:193], v113 offset:26624
	ds_read_b64_tr_b16 v[194:195], v113 offset:27136
	ds_read_b64_tr_b16 v[220:221], v113 offset:30720
	ds_read_b64_tr_b16 v[222:223], v113 offset:31232
	ds_read_b64_tr_b16 v[224:225], v113 offset:19456
	ds_read_b64_tr_b16 v[226:227], v113 offset:19968
	ds_read_b64_tr_b16 v[228:229], v113 offset:23552
	ds_read_b64_tr_b16 v[230:231], v113 offset:24064
	ds_read_b64_tr_b16 v[232:233], v113 offset:27648
	ds_read_b64_tr_b16 v[234:235], v113 offset:28160
	ds_read_b64_tr_b16 v[246:247], v113 offset:31744
	ds_read_b64_tr_b16 v[248:249], v113 offset:32256
	v_cvt_pk_bf16_f32 v134, v126, v127
	v_cvt_pk_bf16_f32 v135, v128, v129
	s_mov_b32 s38, s36
	s_mov_b32 s39, s36
	s_mov_b32 s37, s36
	v_mov_b64_e32 v[198:199], s[38:39]
	v_mov_b64_e32 v[196:197], s[36:37]
	v_cvt_pk_bf16_f32 v200, v118, v119
	v_cvt_pk_bf16_f32 v201, v120, v121
	v_cvt_pk_bf16_f32 v202, v114, v115
	v_cvt_pk_bf16_f32 v203, v116, v117
	v_mov_b32_e32 v114, 0
	v_dot2c_f32_bf16_e32 v114, v134, v196
	v_dot2c_f32_bf16_e32 v114, v135, v196
	v_dot2c_f32_bf16_e32 v114, v136, v196
	v_dot2c_f32_bf16_e32 v114, v137, v196
	s_waitcnt lgkmcnt(14)
	v_mfma_f32_32x32x16_bf16 v[64:79], v[130:133], v[134:137], v[64:79]
	ds_read_b64_tr_b16 v[130:131], v113 offset:20480
	ds_read_b64_tr_b16 v[132:133], v113 offset:20992
	s_waitcnt lgkmcnt(14)
	v_mfma_f32_32x32x16_bf16 v[48:63], v[138:141], v[134:137], v[48:63]
	ds_read_b64_tr_b16 v[138:139], v113 offset:24576
	ds_read_b64_tr_b16 v[140:141], v113 offset:25088
	s_waitcnt lgkmcnt(14)
	v_mfma_f32_32x32x16_bf16 v[32:47], v[192:195], v[134:137], v[32:47]
	ds_read_b64_tr_b16 v[192:193], v113 offset:28672
	ds_read_b64_tr_b16 v[194:195], v113 offset:29184
	v_exp_f32_e32 v142, v80
	v_exp_f32_e32 v143, v81
	v_exp_f32_e32 v219, v82
	v_exp_f32_e32 v236, v83
	s_waitcnt lgkmcnt(14)
	v_mfma_f32_32x32x16_bf16 v[16:31], v[220:223], v[134:137], v[16:31]
	ds_read_b64_tr_b16 v[80:81], v113 offset:32768
	ds_read_b64_tr_b16 v[82:83], v113 offset:33280
	v_exp_f32_e32 v134, v84
	v_exp_f32_e32 v135, v85
	v_exp_f32_e32 v136, v86
	v_exp_f32_e32 v87, v87
	v_dot2c_f32_bf16_e32 v114, v200, v196
	v_dot2c_f32_bf16_e32 v114, v201, v196
	v_dot2c_f32_bf16_e32 v114, v202, v196
	v_dot2c_f32_bf16_e32 v114, v203, v196
	v_cvt_pk_bf16_f32 v84, v142, v143
	v_cvt_pk_bf16_f32 v85, v219, v236
	v_cvt_pk_bf16_f32 v86, v134, v135
	v_cvt_pk_bf16_f32 v87, v136, v87
	s_waitcnt lgkmcnt(14)
	v_mfma_f32_32x32x16_bf16 v[64:79], v[224:227], v[200:203], v[64:79]
	ds_read_b64_tr_b16 v[134:135], v113 offset:21504
	ds_read_b64_tr_b16 v[136:137], v113 offset:22016
	s_waitcnt lgkmcnt(14)
	v_mfma_f32_32x32x16_bf16 v[48:63], v[228:231], v[200:203], v[48:63]
	ds_read_b64_tr_b16 v[220:221], v113 offset:25600
	ds_read_b64_tr_b16 v[222:223], v113 offset:26112
	s_waitcnt lgkmcnt(14)
	v_mfma_f32_32x32x16_bf16 v[32:47], v[232:235], v[200:203], v[32:47]
	ds_read_b64_tr_b16 v[224:225], v113 offset:29696
	ds_read_b64_tr_b16 v[226:227], v113 offset:30208
	v_exp_f32_e32 v142, v88
	v_exp_f32_e32 v143, v89
	v_exp_f32_e32 v219, v90
	v_exp_f32_e32 v228, v91
	s_waitcnt lgkmcnt(14)
	v_mfma_f32_32x32x16_bf16 v[16:31], v[246:249], v[200:203], v[16:31]
	ds_read_b64_tr_b16 v[88:89], v113 offset:33792
	ds_read_b64_tr_b16 v[90:91], v113 offset:34304
	v_exp_f32_e32 v200, v92
	v_exp_f32_e32 v201, v93
	v_exp_f32_e32 v202, v94
	v_exp_f32_e32 v95, v95
	v_dot2c_f32_bf16_e32 v114, v84, v196
	v_dot2c_f32_bf16_e32 v114, v85, v196
	v_dot2c_f32_bf16_e32 v114, v86, v196
	v_dot2c_f32_bf16_e32 v114, v87, v196
	v_cvt_pk_bf16_f32 v92, v142, v143
	v_cvt_pk_bf16_f32 v93, v219, v228
	v_cvt_pk_bf16_f32 v94, v200, v201
	v_cvt_pk_bf16_f32 v95, v202, v95
	s_waitcnt lgkmcnt(14)
	v_mfma_f32_32x32x16_bf16 v[64:79], v[130:133], v[84:87], v[64:79]
	s_waitcnt lgkmcnt(12)
	v_mfma_f32_32x32x16_bf16 v[48:63], v[138:141], v[84:87], v[48:63]
	s_waitcnt lgkmcnt(10)
	v_mfma_f32_32x32x16_bf16 v[32:47], v[192:195], v[84:87], v[32:47]
	s_waitcnt lgkmcnt(8)
	v_mfma_f32_32x32x16_bf16 v[16:31], v[80:83], v[84:87], v[16:31]
	v_dot2c_f32_bf16_e32 v114, v92, v196
	v_dot2c_f32_bf16_e32 v114, v93, v196
	v_dot2c_f32_bf16_e32 v114, v94, v196
	v_dot2c_f32_bf16_e32 v114, v95, v196
	s_nop 2
	v_mov_b32_e32 v115, v114
	s_nop 1
	v_permlane32_swap_b32_e32 v114, v115
	v_add_f32_e32 v114, v114, v115
	s_and_saveexec_b64 s[0:1], s[44:45]
	s_cbranch_execz .LBB0_936
	s_waitcnt vmcnt(2)
	ds_write_b128 v207, v[2:5]

.LBB0_951:
	ds_read_b64_tr_b16 v[192:193], v113 offset:34816
	ds_read_b64_tr_b16 v[194:195], v113 offset:35328
	ds_read_b64_tr_b16 v[196:197], v113 offset:38912
	ds_read_b64_tr_b16 v[198:199], v113 offset:39424
	ds_read_b64_tr_b16 v[200:201], v113 offset:43008
	ds_read_b64_tr_b16 v[202:203], v113 offset:43520
	ds_read_b64_tr_b16 v[220:221], v113 offset:47104
	ds_read_b64_tr_b16 v[222:223], v113 offset:47616
	ds_read_b64_tr_b16 v[224:225], v113 offset:35840
	ds_read_b64_tr_b16 v[226:227], v113 offset:36352
	ds_read_b64_tr_b16 v[228:229], v113 offset:39936
	ds_read_b64_tr_b16 v[230:231], v113 offset:40448
	ds_read_b64_tr_b16 v[232:233], v113 offset:44032
	ds_read_b64_tr_b16 v[234:235], v113 offset:44544
	ds_read_b64_tr_b16 v[246:247], v113 offset:48128
	ds_read_b64_tr_b16 v[248:249], v113 offset:48640
	v_cvt_pk_bf16_f32 v124, v144, v145
	v_cvt_pk_bf16_f32 v125, v146, v147
	v_cvt_pk_bf16_f32 v126, v148, v149
	v_cvt_pk_bf16_f32 v127, v150, v151
	s_mov_b32 s38, s36
	s_mov_b32 s39, s36
	s_mov_b32 s37, s36
	v_mov_b64_e32 v[244:245], s[38:39]
	v_mov_b64_e32 v[242:243], s[36:37]
	v_cvt_pk_bf16_f32 v120, v120, v121
	v_cvt_pk_bf16_f32 v121, v122, v123
	v_mov_b32_e32 v144, 0
	v_dot2c_f32_bf16_e32 v144, v124, v242
	v_dot2c_f32_bf16_e32 v144, v125, v242
	v_dot2c_f32_bf16_e32 v144, v126, v242
	v_dot2c_f32_bf16_e32 v144, v127, v242
	v_cvt_pk_bf16_f32 v122, v116, v117
	v_cvt_pk_bf16_f32 v123, v118, v119
	s_waitcnt lgkmcnt(14)
	v_mfma_f32_32x32x16_bf16 v[64:79], v[192:195], v[124:127], v[64:79]
	ds_read_b64_tr_b16 v[116:117], v113 offset:36864
	ds_read_b64_tr_b16 v[118:119], v113 offset:37376
	s_waitcnt lgkmcnt(14)
	v_mfma_f32_32x32x16_bf16 v[48:63], v[196:199], v[124:127], v[48:63]
	ds_read_b64_tr_b16 v[192:193], v113 offset:40960
	ds_read_b64_tr_b16 v[194:195], v113 offset:41472
	s_waitcnt lgkmcnt(14)
	v_mfma_f32_32x32x16_bf16 v[32:47], v[200:203], v[124:127], v[32:47]
	ds_read_b64_tr_b16 v[196:197], v113 offset:45056
	ds_read_b64_tr_b16 v[198:199], v113 offset:45568
	v_exp_f32_e32 v200, v96
	v_exp_f32_e32 v201, v97
	v_exp_f32_e32 v202, v98
	v_exp_f32_e32 v203, v99
	s_waitcnt lgkmcnt(14)
	v_mfma_f32_32x32x16_bf16 v[16:31], v[220:223], v[124:127], v[16:31]
	ds_read_b64_tr_b16 v[96:97], v113 offset:49152
	ds_read_b64_tr_b16 v[98:99], v113 offset:49664
	v_exp_f32_e32 v124, v100
	v_exp_f32_e32 v125, v101
	v_exp_f32_e32 v126, v102
	v_exp_f32_e32 v103, v103
	v_dot2c_f32_bf16_e32 v144, v120, v242
	v_dot2c_f32_bf16_e32 v144, v121, v242
	v_dot2c_f32_bf16_e32 v144, v122, v242
	v_dot2c_f32_bf16_e32 v144, v123, v242
	v_cvt_pk_bf16_f32 v100, v200, v201
	v_cvt_pk_bf16_f32 v101, v202, v203
	v_cvt_pk_bf16_f32 v102, v124, v125
	v_cvt_pk_bf16_f32 v103, v126, v103
	s_waitcnt lgkmcnt(14)
	v_mfma_f32_32x32x16_bf16 v[64:79], v[224:227], v[120:123], v[64:79]
	ds_read_b64_tr_b16 v[124:125], v113 offset:37888
	ds_read_b64_tr_b16 v[126:127], v113 offset:38400
	s_waitcnt lgkmcnt(14)
	v_mfma_f32_32x32x16_bf16 v[48:63], v[228:231], v[120:123], v[48:63]
	ds_read_b64_tr_b16 v[200:201], v113 offset:41984
	ds_read_b64_tr_b16 v[202:203], v113 offset:42496
	s_waitcnt lgkmcnt(14)
	v_mfma_f32_32x32x16_bf16 v[32:47], v[232:235], v[120:123], v[32:47]
	ds_read_b64_tr_b16 v[220:221], v113 offset:46080
	ds_read_b64_tr_b16 v[222:223], v113 offset:46592
	v_exp_f32_e32 v219, v104
	v_exp_f32_e32 v224, v105
	v_exp_f32_e32 v225, v106
	v_exp_f32_e32 v226, v107
	s_waitcnt lgkmcnt(14)
	v_mfma_f32_32x32x16_bf16 v[16:31], v[246:249], v[120:123], v[16:31]
	ds_read_b64_tr_b16 v[104:105], v113 offset:50176
	ds_read_b64_tr_b16 v[106:107], v113 offset:50688
	v_exp_f32_e32 v120, v108
	v_exp_f32_e32 v121, v109
	v_exp_f32_e32 v122, v110
	v_exp_f32_e32 v111, v111
	v_dot2c_f32_bf16_e32 v144, v100, v242
	v_dot2c_f32_bf16_e32 v144, v101, v242
	v_dot2c_f32_bf16_e32 v144, v102, v242
	v_dot2c_f32_bf16_e32 v144, v103, v242
	v_cvt_pk_bf16_f32 v108, v219, v224
	v_cvt_pk_bf16_f32 v109, v225, v226
	v_cvt_pk_bf16_f32 v110, v120, v121
	v_cvt_pk_bf16_f32 v111, v122, v111
	s_waitcnt lgkmcnt(14)
	v_mfma_f32_32x32x16_bf16 v[64:79], v[116:119], v[100:103], v[64:79]
	s_waitcnt lgkmcnt(12)
	v_mfma_f32_32x32x16_bf16 v[48:63], v[192:195], v[100:103], v[48:63]
	s_waitcnt lgkmcnt(10)
	v_mfma_f32_32x32x16_bf16 v[32:47], v[196:199], v[100:103], v[32:47]
	s_waitcnt lgkmcnt(8)
	v_mfma_f32_32x32x16_bf16 v[16:31], v[96:99], v[100:103], v[16:31]
	v_dot2c_f32_bf16_e32 v144, v108, v242
	v_dot2c_f32_bf16_e32 v144, v109, v242
	v_dot2c_f32_bf16_e32 v144, v110, v242
	v_dot2c_f32_bf16_e32 v144, v111, v242
	s_nop 2
	v_mov_b32_e32 v145, v144
	s_nop 1
	v_permlane32_swap_b32_e32 v144, v145
	v_add_f32_e32 v144, v144, v145
	s_and_saveexec_b64 s[0:1], s[44:45]
	s_cbranch_execz .LBB0_953
	s_waitcnt vmcnt(2)
	ds_write_b128 v207, v[2:5] offset:9216

.LBB0_980:
	v_cvt_pk_bf16_f32 v136, v130, v131
	v_cvt_pk_bf16_f32 v137, v132, v133
	ds_read_b64_tr_b16 v[130:131], v113 offset:18432
	ds_read_b64_tr_b16 v[132:133], v113 offset:18944
	ds_read_b64_tr_b16 v[138:139], v113 offset:22528
	ds_read_b64_tr_b16 v[140:141], v113 offset:23040
	ds_read_b64_tr_b16 v[192:193], v113 offset:26624
	ds_read_b64_tr_b16 v[194:195], v113 offset:27136
	ds_read_b64_tr_b16 v[196:197], v113 offset:30720
	ds_read_b64_tr_b16 v[198:199], v113 offset:31232
	ds_read_b64_tr_b16 v[200:201], v113 offset:19456
	ds_read_b64_tr_b16 v[202:203], v113 offset:19968
	ds_read_b64_tr_b16 v[220:221], v113 offset:23552
	ds_read_b64_tr_b16 v[222:223], v113 offset:24064
	ds_read_b64_tr_b16 v[224:225], v113 offset:27648
	ds_read_b64_tr_b16 v[226:227], v113 offset:28160
	ds_read_b64_tr_b16 v[228:229], v113 offset:31744
	ds_read_b64_tr_b16 v[230:231], v113 offset:32256
	v_cvt_pk_bf16_f32 v134, v126, v127
	v_cvt_pk_bf16_f32 v135, v128, v129
	s_mov_b32 s38, s36
	s_mov_b32 s39, s36
	s_mov_b32 s37, s36
	v_mov_b64_e32 v[234:235], s[38:39]
	v_mov_b64_e32 v[232:233], s[36:37]
	v_cvt_pk_bf16_f32 v242, v118, v119
	v_cvt_pk_bf16_f32 v243, v120, v121
	v_cvt_pk_bf16_f32 v244, v114, v115
	v_cvt_pk_bf16_f32 v245, v116, v117
	v_mov_b32_e32 v114, 0
	v_dot2c_f32_bf16_e32 v114, v134, v232
	v_dot2c_f32_bf16_e32 v114, v135, v232
	v_dot2c_f32_bf16_e32 v114, v136, v232
	v_dot2c_f32_bf16_e32 v114, v137, v232
	s_waitcnt lgkmcnt(14)
	v_mfma_f32_32x32x16_bf16 v[64:79], v[130:133], v[134:137], v[64:79]
	ds_read_b64_tr_b16 v[130:131], v113 offset:20480
	ds_read_b64_tr_b16 v[132:133], v113 offset:20992
	s_waitcnt lgkmcnt(14)
	v_mfma_f32_32x32x16_bf16 v[48:63], v[138:141], v[134:137], v[48:63]
	ds_read_b64_tr_b16 v[138:139], v113 offset:24576
	ds_read_b64_tr_b16 v[140:141], v113 offset:25088
	s_waitcnt lgkmcnt(14)
	v_mfma_f32_32x32x16_bf16 v[32:47], v[192:195], v[134:137], v[32:47]
	ds_read_b64_tr_b16 v[192:193], v113 offset:28672
	ds_read_b64_tr_b16 v[194:195], v113 offset:29184
	v_exp_f32_e32 v142, v80
	v_exp_f32_e32 v143, v81
	v_exp_f32_e32 v219, v82
	v_exp_f32_e32 v236, v83
	s_waitcnt lgkmcnt(14)
	v_mfma_f32_32x32x16_bf16 v[16:31], v[196:199], v[134:137], v[16:31]
	ds_read_b64_tr_b16 v[80:81], v113 offset:32768
	ds_read_b64_tr_b16 v[82:83], v113 offset:33280
	v_exp_f32_e32 v134, v84
	v_exp_f32_e32 v135, v85
	v_exp_f32_e32 v136, v86
	v_exp_f32_e32 v87, v87
	v_dot2c_f32_bf16_e32 v114, v242, v232
	v_dot2c_f32_bf16_e32 v114, v243, v232
	v_dot2c_f32_bf16_e32 v114, v244, v232
	v_dot2c_f32_bf16_e32 v114, v245, v232
	v_cvt_pk_bf16_f32 v84, v142, v143
	v_cvt_pk_bf16_f32 v85, v219, v236
	v_cvt_pk_bf16_f32 v86, v134, v135
	v_cvt_pk_bf16_f32 v87, v136, v87
	s_waitcnt lgkmcnt(14)
	v_mfma_f32_32x32x16_bf16 v[64:79], v[200:203], v[242:245], v[64:79]
	ds_read_b64_tr_b16 v[134:135], v113 offset:21504
	ds_read_b64_tr_b16 v[136:137], v113 offset:22016
	s_waitcnt lgkmcnt(14)
	v_mfma_f32_32x32x16_bf16 v[48:63], v[220:223], v[242:245], v[48:63]
	ds_read_b64_tr_b16 v[196:197], v113 offset:25600
	ds_read_b64_tr_b16 v[198:199], v113 offset:26112
	s_waitcnt lgkmcnt(14)
	v_mfma_f32_32x32x16_bf16 v[32:47], v[224:227], v[242:245], v[32:47]
	ds_read_b64_tr_b16 v[200:201], v113 offset:29696
	ds_read_b64_tr_b16 v[202:203], v113 offset:30208
	v_exp_f32_e32 v142, v88
	v_exp_f32_e32 v143, v89
	v_exp_f32_e32 v219, v90
	v_exp_f32_e32 v220, v91
	s_waitcnt lgkmcnt(14)
	v_mfma_f32_32x32x16_bf16 v[16:31], v[228:231], v[242:245], v[16:31]
	ds_read_b64_tr_b16 v[88:89], v113 offset:33792
	ds_read_b64_tr_b16 v[90:91], v113 offset:34304
	v_exp_f32_e32 v221, v92
	v_exp_f32_e32 v222, v93
	v_exp_f32_e32 v223, v94
	v_exp_f32_e32 v95, v95
	v_dot2c_f32_bf16_e32 v114, v84, v232
	v_dot2c_f32_bf16_e32 v114, v85, v232
	v_dot2c_f32_bf16_e32 v114, v86, v232
	v_dot2c_f32_bf16_e32 v114, v87, v232
	v_cvt_pk_bf16_f32 v92, v142, v143
	v_cvt_pk_bf16_f32 v93, v219, v220
	v_cvt_pk_bf16_f32 v94, v221, v222
	v_cvt_pk_bf16_f32 v95, v223, v95
	s_waitcnt lgkmcnt(14)
	v_mfma_f32_32x32x16_bf16 v[64:79], v[130:133], v[84:87], v[64:79]
	s_waitcnt lgkmcnt(12)
	v_mfma_f32_32x32x16_bf16 v[48:63], v[138:141], v[84:87], v[48:63]
	s_waitcnt lgkmcnt(10)
	v_mfma_f32_32x32x16_bf16 v[32:47], v[192:195], v[84:87], v[32:47]
	s_waitcnt lgkmcnt(8)
	v_mfma_f32_32x32x16_bf16 v[16:31], v[80:83], v[84:87], v[16:31]
	v_dot2c_f32_bf16_e32 v114, v92, v232
	v_dot2c_f32_bf16_e32 v114, v93, v232
	v_dot2c_f32_bf16_e32 v114, v94, v232
	v_dot2c_f32_bf16_e32 v114, v95, v232
	s_nop 2
	v_mov_b32_e32 v115, v114
	s_nop 1
	v_permlane32_swap_b32_e32 v114, v115
	v_add_f32_e32 v114, v114, v115
	s_and_saveexec_b64 s[0:1], s[44:45]
	s_cbranch_execz .LBB0_982
	s_waitcnt vmcnt(2)
	ds_write_b128 v207, v[2:5]

.LBB0_997:
	ds_read_b64_tr_b16 v[192:193], v113 offset:34816
	ds_read_b64_tr_b16 v[194:195], v113 offset:35328
	ds_read_b64_tr_b16 v[196:197], v113 offset:38912
	ds_read_b64_tr_b16 v[198:199], v113 offset:39424
	ds_read_b64_tr_b16 v[200:201], v113 offset:43008
	ds_read_b64_tr_b16 v[202:203], v113 offset:43520
	ds_read_b64_tr_b16 v[220:221], v113 offset:47104
	ds_read_b64_tr_b16 v[222:223], v113 offset:47616
	ds_read_b64_tr_b16 v[224:225], v113 offset:35840
	ds_read_b64_tr_b16 v[226:227], v113 offset:36352
	ds_read_b64_tr_b16 v[228:229], v113 offset:39936
	ds_read_b64_tr_b16 v[230:231], v113 offset:40448
	ds_read_b64_tr_b16 v[232:233], v113 offset:44032
	ds_read_b64_tr_b16 v[234:235], v113 offset:44544
	ds_read_b64_tr_b16 v[242:243], v113 offset:48128
	ds_read_b64_tr_b16 v[244:245], v113 offset:48640
	v_cvt_pk_bf16_f32 v124, v144, v145
	v_cvt_pk_bf16_f32 v125, v146, v147
	v_cvt_pk_bf16_f32 v126, v148, v149
	v_cvt_pk_bf16_f32 v127, v150, v151
	s_mov_b32 s38, s36
	s_mov_b32 s39, s36
	s_mov_b32 s37, s36
	v_mov_b64_e32 v[248:249], s[38:39]
	v_mov_b64_e32 v[246:247], s[36:37]
	v_cvt_pk_bf16_f32 v120, v120, v121
	v_cvt_pk_bf16_f32 v121, v122, v123
	v_mov_b32_e32 v144, 0
	v_dot2c_f32_bf16_e32 v144, v124, v246
	v_dot2c_f32_bf16_e32 v144, v125, v246
	v_dot2c_f32_bf16_e32 v144, v126, v246
	v_dot2c_f32_bf16_e32 v144, v127, v246
	v_cvt_pk_bf16_f32 v122, v116, v117
	v_cvt_pk_bf16_f32 v123, v118, v119
	s_waitcnt lgkmcnt(14)
	v_mfma_f32_32x32x16_bf16 v[64:79], v[192:195], v[124:127], v[64:79]
	ds_read_b64_tr_b16 v[116:117], v113 offset:36864
	ds_read_b64_tr_b16 v[118:119], v113 offset:37376
	s_waitcnt lgkmcnt(14)
	v_mfma_f32_32x32x16_bf16 v[48:63], v[196:199], v[124:127], v[48:63]
	ds_read_b64_tr_b16 v[192:193], v113 offset:40960
	ds_read_b64_tr_b16 v[194:195], v113 offset:41472
	s_waitcnt lgkmcnt(14)
	v_mfma_f32_32x32x16_bf16 v[32:47], v[200:203], v[124:127], v[32:47]
	ds_read_b64_tr_b16 v[196:197], v113 offset:45056
	ds_read_b64_tr_b16 v[198:199], v113 offset:45568
	v_exp_f32_e32 v200, v96
	v_exp_f32_e32 v201, v97
	v_exp_f32_e32 v202, v98
	v_exp_f32_e32 v203, v99
	s_waitcnt lgkmcnt(14)
	v_mfma_f32_32x32x16_bf16 v[16:31], v[220:223], v[124:127], v[16:31]
	ds_read_b64_tr_b16 v[96:97], v113 offset:49152
	ds_read_b64_tr_b16 v[98:99], v113 offset:49664
	v_exp_f32_e32 v124, v100
	v_exp_f32_e32 v125, v101
	v_exp_f32_e32 v126, v102
	v_exp_f32_e32 v103, v103
	v_dot2c_f32_bf16_e32 v144, v120, v246
	v_dot2c_f32_bf16_e32 v144, v121, v246
	v_dot2c_f32_bf16_e32 v144, v122, v246
	v_dot2c_f32_bf16_e32 v144, v123, v246
	v_cvt_pk_bf16_f32 v100, v200, v201
	v_cvt_pk_bf16_f32 v101, v202, v203
	v_cvt_pk_bf16_f32 v102, v124, v125
	v_cvt_pk_bf16_f32 v103, v126, v103
	s_waitcnt lgkmcnt(14)
	v_mfma_f32_32x32x16_bf16 v[64:79], v[224:227], v[120:123], v[64:79]
	ds_read_b64_tr_b16 v[124:125], v113 offset:37888
	ds_read_b64_tr_b16 v[126:127], v113 offset:38400
	s_waitcnt lgkmcnt(14)
	v_mfma_f32_32x32x16_bf16 v[48:63], v[228:231], v[120:123], v[48:63]
	ds_read_b64_tr_b16 v[200:201], v113 offset:41984
	ds_read_b64_tr_b16 v[202:203], v113 offset:42496
	s_waitcnt lgkmcnt(14)
	v_mfma_f32_32x32x16_bf16 v[32:47], v[232:235], v[120:123], v[32:47]
	ds_read_b64_tr_b16 v[220:221], v113 offset:46080
	ds_read_b64_tr_b16 v[222:223], v113 offset:46592
	v_exp_f32_e32 v219, v104
	v_exp_f32_e32 v224, v105
	v_exp_f32_e32 v225, v106
	v_exp_f32_e32 v226, v107
	s_waitcnt lgkmcnt(14)
	v_mfma_f32_32x32x16_bf16 v[16:31], v[242:245], v[120:123], v[16:31]
	ds_read_b64_tr_b16 v[104:105], v113 offset:50176
	ds_read_b64_tr_b16 v[106:107], v113 offset:50688
	v_exp_f32_e32 v120, v108
	v_exp_f32_e32 v121, v109
	v_exp_f32_e32 v122, v110
	v_exp_f32_e32 v111, v111
	v_dot2c_f32_bf16_e32 v144, v100, v246
	v_dot2c_f32_bf16_e32 v144, v101, v246
	v_dot2c_f32_bf16_e32 v144, v102, v246
	v_dot2c_f32_bf16_e32 v144, v103, v246
	v_cvt_pk_bf16_f32 v108, v219, v224
	v_cvt_pk_bf16_f32 v109, v225, v226
	v_cvt_pk_bf16_f32 v110, v120, v121
	v_cvt_pk_bf16_f32 v111, v122, v111
	s_waitcnt lgkmcnt(14)
	v_mfma_f32_32x32x16_bf16 v[64:79], v[116:119], v[100:103], v[64:79]
	s_waitcnt lgkmcnt(12)
	v_mfma_f32_32x32x16_bf16 v[48:63], v[192:195], v[100:103], v[48:63]
	s_waitcnt lgkmcnt(10)
	v_mfma_f32_32x32x16_bf16 v[32:47], v[196:199], v[100:103], v[32:47]
	s_waitcnt lgkmcnt(8)
	v_mfma_f32_32x32x16_bf16 v[16:31], v[96:99], v[100:103], v[16:31]
	v_dot2c_f32_bf16_e32 v144, v108, v246
	v_dot2c_f32_bf16_e32 v144, v109, v246
	v_dot2c_f32_bf16_e32 v144, v110, v246
	v_dot2c_f32_bf16_e32 v144, v111, v246
	s_nop 2
	v_mov_b32_e32 v145, v144
	s_nop 1
	v_permlane32_swap_b32_e32 v144, v145
	v_add_f32_e32 v144, v144, v145
	s_and_saveexec_b64 s[0:1], s[44:45]
	s_cbranch_execz .LBB0_999
	s_waitcnt vmcnt(2)
	ds_write_b128 v207, v[10:13] offset:9216
